# v12: same as v8 (W1 split, W1 L2 prefetch, batched epilogue/tile loads, gla_pass3 item redistribution) with grid-size guards falling back to the original mapping
# speedup vs baseline: 1.0025x; 1.0025x over previous
; #define LDSP(T, p) ((__attribute__((address_space(3))) T*)(p))
; DI int tidx() { int t = threadIdx.x; asm volatile("" : "+v"(t)); return t; }
; DI void gemm_issue_first(const bf16_t* __restrict__ A, int lda, const bf16_t* __restrict__ Bt, int ldb, int m0, int n0, char* smem) {
;   const int tid = tidx(), wave = tid >> 6, lane = tid & 63;
; #pragma unroll
;   for (int i = 0; i < 4; ++i) {
;     const int row = (i * 4 + wave) * 8 + (lane >> 3), chunk = (lane & 7) ^ ((row >> 1) & 7);
;     __builtin_amdgcn_global_load_lds((const unsigned*)(A + (size_t)(m0 + row) * lda + chunk * 8), LDSP(unsigned, smem + (i * 4 + wave) * 1024), 16, 0, 0);
;     __builtin_amdgcn_global_load_lds((const unsigned*)(Bt + (size_t)(n0 + row) * ldb + chunk * 8), LDSP(unsigned, smem + 16384 + (i * 4 + wave) * 1024), 16, 0, 0);
;   }
; }
; __global__ void __launch_bounds__(256, 2) mega(Params p) {
;     ...
;       ga = GArgs{}; ga.A = aflk; ga.lda = 4096; ga.Bt = (bf16_t*)(ws + W_W1) + (size_t)(j * 2) * 128 * 4096; ga.K = 4096; ga.M = 2048; ga.Npad = 128; ga.C = hck; ga.ldc = 128;
;       gemm_phase<EPI_GELU>(ga, smem);
.LBB0_356:
	v_mov_b32_e32 v2, v190
	v_readlane_b32 s101, v253, 52
	s_cmpk_lt_u32 s101, 0x90
	s_cselect_b32 s101, 0, 0x80
	s_sub_u32 s100, s82, s101
	s_cmp_gt_u32 s100, 15
	s_cbranch_scc1 .LBB0_367
	v_mov_b32_e32 v3, v190
	v_readlane_b32 s3, v253, 8
	v_ashrrev_i32_e32 v6, 6, v3
	v_bfe_u32 v7, v3, 3, 3
	v_lshl_or_b32 v8, v6, 3, v7
	v_lshrrev_b32_e32 v0, 1, v8
	v_add_u32_e32 v4, s3, v8
	s_lshl_b64 s[0:1], s[80:81], 13
	v_readlane_b32 s2, v250, 58
	v_xor_b32_e32 v0, v0, v3
	v_ashrrev_i32_e32 v5, 31, v4
	v_readlane_b32 s4, v252, 57
	s_add_u32 s0, s2, s0
	v_readlane_b32 s2, v250, 59
	v_lshlrev_b64 v[4:5], 13, v[4:5]
	v_readlane_b32 s5, v252, 58
	v_lshlrev_b32_e32 v0, 4, v0
	v_lshlrev_b32_e32 v9, 10, v6
	s_addc_u32 s1, s2, s1
	v_lshl_add_u64 v[4:5], s[4:5], 0, v[4:5]
	v_and_b32_e32 v0, 0x70, v0
	v_readfirstlane_b32 s2, v9
	v_lshl_add_u64 v[4:5], v[4:5], 0, v[0:1]
	s_mov_b32 m0, s2
	s_mov_b32 s6, 0
	global_load_lds_dwordx4 v[4:5], off
	s_nop 0
	v_add_u32_e32 v4, s6, v8
	v_ashrrev_i32_e32 v5, 31, v4
	v_lshlrev_b64 v[4:5], 13, v[4:5]
	v_lshl_add_u64 v[4:5], s[0:1], 0, v[4:5]
	v_lshl_add_u64 v[4:5], v[4:5], 0, v[0:1]
	v_add_u32_e32 v0, 0x4000, v9
	v_add_u32_e32 v8, 4, v6
	v_readfirstlane_b32 s2, v0
	s_mov_b32 m0, s2
	v_lshl_or_b32 v9, v8, 3, v7
	global_load_lds_dwordx4 v[4:5], off
	v_lshrrev_b32_e32 v0, 1, v9
	v_add_u32_e32 v4, s3, v9
	v_xor_b32_e32 v0, v0, v3
	v_ashrrev_i32_e32 v5, 31, v4
	v_lshlrev_b64 v[4:5], 13, v[4:5]
	v_lshlrev_b32_e32 v0, 4, v0
	v_lshlrev_b32_e32 v8, 10, v8
	v_lshl_add_u64 v[4:5], s[4:5], 0, v[4:5]
	v_and_b32_e32 v0, 0x70, v0
	v_readfirstlane_b32 s2, v8
	v_lshl_add_u64 v[4:5], v[4:5], 0, v[0:1]
	s_mov_b32 m0, s2
	s_nop 0
	global_load_lds_dwordx4 v[4:5], off
	v_add_u32_e32 v4, s6, v9
	v_ashrrev_i32_e32 v5, 31, v4
	v_lshlrev_b64 v[4:5], 13, v[4:5]
	v_lshl_add_u64 v[4:5], s[0:1], 0, v[4:5]
	v_lshl_add_u64 v[4:5], v[4:5], 0, v[0:1]
	v_add_u32_e32 v0, 0x4000, v8
	v_add_u32_e32 v8, 8, v6
	v_readfirstlane_b32 s2, v0
	s_mov_b32 m0, s2
	v_lshl_or_b32 v9, v8, 3, v7
	global_load_lds_dwordx4 v[4:5], off
	v_lshrrev_b32_e32 v0, 1, v9
	v_add_u32_e32 v4, s3, v9
	v_xor_b32_e32 v0, v0, v3
	v_ashrrev_i32_e32 v5, 31, v4
	v_lshlrev_b64 v[4:5], 13, v[4:5]
	v_lshlrev_b32_e32 v0, 4, v0
	v_lshlrev_b32_e32 v8, 10, v8
	v_lshl_add_u64 v[4:5], s[4:5], 0, v[4:5]
	v_and_b32_e32 v0, 0x70, v0
	v_readfirstlane_b32 s2, v8
	v_lshl_add_u64 v[4:5], v[4:5], 0, v[0:1]
	s_mov_b32 m0, s2
	v_add_u32_e32 v6, 12, v6
	global_load_lds_dwordx4 v[4:5], off
	v_add_u32_e32 v4, s6, v9
	v_ashrrev_i32_e32 v5, 31, v4
	v_lshlrev_b64 v[4:5], 13, v[4:5]
	v_lshl_add_u64 v[4:5], s[0:1], 0, v[4:5]
	v_lshl_add_u64 v[4:5], v[4:5], 0, v[0:1]
	v_add_u32_e32 v0, 0x4000, v8
	v_lshl_or_b32 v7, v6, 3, v7
	v_readfirstlane_b32 s2, v0
	s_mov_b32 m0, s2
	v_lshrrev_b32_e32 v0, 1, v7
	global_load_lds_dwordx4 v[4:5], off
	v_add_u32_e32 v4, s3, v7
	v_xor_b32_e32 v0, v0, v3
	v_ashrrev_i32_e32 v5, 31, v4
	v_lshlrev_b64 v[4:5], 13, v[4:5]
	v_lshlrev_b32_e32 v0, 4, v0
	v_lshlrev_b32_e32 v3, 10, v6
	v_lshl_add_u64 v[4:5], s[4:5], 0, v[4:5]
	v_and_b32_e32 v0, 0x70, v0
	v_readfirstlane_b32 s2, v3
	v_lshl_add_u64 v[4:5], v[4:5], 0, v[0:1]
	s_mov_b32 m0, s2
	s_mov_b32 s4, s100
	global_load_lds_dwordx4 v[4:5], off
	v_add_u32_e32 v4, s6, v7
	v_ashrrev_i32_e32 v5, 31, v4
	v_lshlrev_b64 v[4:5], 13, v[4:5]
	v_lshl_add_u64 v[4:5], s[0:1], 0, v[4:5]
	v_lshl_add_u64 v[4:5], v[4:5], 0, v[0:1]
	v_add_u32_e32 v0, 0x4000, v3
	v_and_b32_e32 v3, 15, v2
	v_readfirstlane_b32 s2, v0
	s_mov_b32 m0, s2
	v_ashrrev_i32_e32 v0, 1, v2
	global_load_lds_dwordx4 v[4:5], off
	s_movk_i32 s2, 0xffe0
	v_and_or_b32 v166, v0, s2, v3
	v_lshrrev_b32_e32 v0, 2, v2
	v_and_b32_e32 v167, 12, v0
	s_branch .LBB0_359

; DI unsigned pack2(float lo, float hi) { unsigned r; asm("v_cvt_pk_bf16_f32 %0, %1, %2" : "=v"(r) : "v"(lo), "v"(hi)); return r; }
; DI void load_tile_v(int tid, const bf16_t* __restrict__ g, int ld, char* dst) { u32x4 r[4]; ldg_tile(tid, g, ld, r); sts_tile_v(tid, r, dst); }
; DI void gla_pass3(int item, const bf16_t* __restrict__ z, const float* __restrict__ w_up, const float* __restrict__ b_alpha,
;                   const float* __restrict__ Sbuf, const float* __restrict__ gw, bf16_t* __restrict__ mix, char* smem) {
;     ...
;     if (tj <= ti) {
; #pragma unroll 4
;       for (int d = 0; d < 64; ++d) {
;         const f32x4 qv = *(const f32x4*)(qdT + d * 68 + ti * 4);
;         const f32x4 kv = *(const f32x4*)(kiT + d * 68 + tj * 4);
; #pragma unroll
;         for (int i = 0; i < 4; ++i)
; #pragma unroll
;           for (int j = 0; j < 4; ++j) a4[i][j] += qv[i] * kv[j];
;       }
;     }
; #pragma unroll
;     for (int kt = 0; kt < 4; ++kt)
; #pragma unroll
;       for (int r = 0; r < 4; ++r) sq[kt][0][r] = qdT[(kt * 16 + 4 * g + r) * 68 + iq];
;     __syncthreads();
; #pragma unroll
;     for (int i = 0; i < 4; ++i) {
;       f32x4 o;
; #pragma unroll
;       for (int j = 0; j < 4; ++j) o[j] = (tj * 4 + j <= ti * 4 + i) ? a4[i][j] : 0.f;
;       *(f32x4*)(kiT + (ti * 4 + i) * 68 + tj * 4) = o;
;     }
;   }
;   load_tile_v(tid, z + tok0 * ABP + ZV + h * 128, ABP, Vs);
;   {
;     const float* Sg = Sbuf + (size_t)item * 64 * 128;
; #pragma unroll
;     for (int i = 0; i < 4; ++i) {
;       const int idx = tid + 256 * i, row = idx >> 4, ch = idx & 15;
;       const f32x4 x0 = *(const f32x4*)(Sg + row * 128 + ch * 8), x1 = *(const f32x4*)(Sg + row * 128 + ch * 8 + 4);
;       u32x4 w; w[0] = pack2(x0[0], x0[1]); w[1] = pack2(x0[2], x0[3]); w[2] = pack2(x1[0], x1[1]); w[3] = pack2(x1[2], x1[3]);
;       *(u32x4*)(Ss + voff(row, ch)) = w;
;     }
;   }
; __global__ void __launch_bounds__(256, 2) mega(Params p) {
;     ...
;       for (int it = blockIdx.x; it < 1024; it += gridDim.x) gla_pass3(it, zb, p.in[8] + (size_t)j * 16 * 512, p.in[9] + (size_t)j * 512, Ubuf, p.in[10] + j * 128, mix, smem);
.LBB0_950:
	s_or_b64 exec, exec, s[0:1]
	v_readlane_b32 s0, v251, 1
	v_readlane_b32 s1, v251, 2
	s_and_b64 vcc, exec, s[0:1]
	s_movk_i32 s4, 0x2100
	s_waitcnt lgkmcnt(0)
	s_barrier
	s_cbranch_vccz .LBB0_960
	v_readlane_b32 s2, v254, 44
	v_readlane_b32 s3, v254, 45
	s_lshl_b64 s[0:1], s[2:3], 15
	v_readlane_b32 s8, v250, 18
	v_readlane_b32 s9, v250, 19
	s_add_u32 s6, s8, s0
	v_readlane_b32 s10, v250, 20
	s_addc_u32 s7, s9, s1
	s_lshl_b64 s[0:1], s[2:3], 11
	v_readlane_b32 s11, v250, 21
	s_add_u32 s8, s10, s0
	s_addc_u32 s9, s11, s1
	s_mov_b32 s1, s97
	s_lshl_b32 s0, s2, 7
	v_readlane_b32 s12, v250, 22
	s_lshl_b64 s[0:1], s[0:1], 2
	v_readlane_b32 s13, v250, 23
	s_add_u32 s10, s12, s0
	s_addc_u32 s11, s13, s1
	v_readlane_b32 s100, v253, 52
	s_cmpk_lg_i32 s100, 0x200
	s_cbranch_scc1 .Lgla3_fallback
	s_lshr_b32 s100, s82, 5
	s_add_i32 s100, s100, 2
	s_lshr_b32 s101, s100, 2
	s_and_b32 s100, s100, 3
	s_mul_i32 s100, s101, s100
	s_add_i32 s12, s101, -1
	s_mul_i32 s12, s12, s101
	s_lshl_b32 s12, s12, 1
	s_add_i32 s12, s12, s100
	s_lshl_b32 s12, s12, 5
	s_and_b32 s100, s82, 31
	s_add_i32 s12, s12, s100
	s_lshl_b32 s101, s101, 5
	s_add_i32 s101, s12, s101
	s_mov_b32 s100, 32
	s_branch .Lgla3_init_done
.Lgla3_fallback:
	s_mov_b32 s12, s82
	s_movk_i32 s101, 0x400
.Lgla3_init_done:
	v_readlane_b32 s14, v250, 24
	v_readlane_b32 s15, v250, 25
	v_readlane_b32 s16, v250, 26
	v_readlane_b32 s17, v250, 27
	v_readlane_b32 s18, v250, 28
	v_readlane_b32 s19, v250, 29
	v_readlane_b32 s20, v250, 30
	v_readlane_b32 s21, v250, 31
	v_readlane_b32 s22, v250, 32
	v_readlane_b32 s23, v250, 33
	s_cmp_ge_i32 s12, s101
	s_cbranch_scc1 .LBB0_960
	s_branch .LBB0_953
.LBB0_952:
	s_or_b64 exec, exec, s[0:1]
	v_lshrrev_b32_e32 v0, 2, v40
	v_and_b32_e32 v41, 12, v0
	v_and_or_b32 v38, v8, -16, v9
	v_mul_u32_u24_e32 v0, 0x110, v41
	v_lshl_add_u32 v0, v38, 2, v0
	v_add_u32_e32 v8, 0x1000, v0
	ds_read2_b32 v[22:23], v0 offset1:68
	ds_read2_b32 v[24:25], v0 offset0:136 offset1:204
	ds_read2_b32 v[26:27], v8 offset0:64 offset1:132
	v_add_u32_e32 v8, 0x1200, v0
	ds_read2_b32 v[28:29], v8 offset0:72 offset1:140
	v_add_u32_e32 v8, 0x2000, v0
	ds_read2_b32 v[14:15], v8 offset0:128 offset1:196
	v_add_u32_e32 v8, 0x2400, v0
	ds_read2_b32 v[16:17], v8 offset0:8 offset1:76
	v_add_u32_e32 v8, 0x3200, v0
	v_add_u32_e32 v0, 0x3400, v0
	ds_read2_b32 v[18:19], v8 offset0:64 offset1:132
	ds_read2_b32 v[20:21], v0 offset0:72 offset1:140
	v_lshlrev_b32_e32 v0, 2, v9
	v_lshlrev_b32_e32 v8, 2, v3
	v_cmp_lt_i32_e64 s[0:1], v0, v8
	v_or_b32_e32 v48, 3, v0
	v_cmp_gt_i32_e32 vcc, v0, v8
	v_cndmask_b32_e64 v43, 0, v37, s[0:1]
	v_cndmask_b32_e64 v44, 0, v34, s[0:1]
	v_cmp_le_i32_e64 s[0:1], v48, v8
	v_cndmask_b32_e64 v42, v36, 0, vcc
	v_or_b32_e32 v36, 1, v8
	v_cndmask_b32_e64 v45, 0, v35, s[0:1]
	s_movk_i32 s0, 0x440
	v_mad_u64_u32 v[34:35], s[0:1], v3, s0, v[2:3]
	v_or_b32_e32 v47, 2, v0
	v_cmp_le_i32_e64 s[0:1], v0, v36
	s_waitcnt lgkmcnt(0)
	s_barrier
	v_cndmask_b32_e64 v32, 0, v32, s[0:1]
	v_cmp_le_i32_e64 s[0:1], v47, v36
	ds_write_b128 v34, v[42:45] offset:17408
	s_nop 0
	v_cndmask_b32_e64 v34, 0, v30, s[0:1]
	v_cmp_le_i32_e64 s[0:1], v48, v36
	s_movk_i32 s5, 0x110
	v_cndmask_b32_e64 v33, v33, 0, vcc
	v_cndmask_b32_e64 v35, 0, v31, s[0:1]
	v_mad_u64_u32 v[36:37], s[0:1], v36, s5, v[2:3]
	ds_write_b128 v36, v[32:35] offset:17408
	v_or_b32_e32 v33, 2, v8
	v_cmp_le_i32_e64 s[0:1], v0, v33
	v_or_b32_e32 v8, 3, v8
	v_cndmask_b32_e64 v32, v10, 0, vcc
	v_cndmask_b32_e64 v30, 0, v12, s[0:1]
	v_cmp_le_i32_e64 s[0:1], v48, v33
	s_movk_i32 s4, 0x2100
	v_cndmask_b32_e64 v31, v13, 0, vcc
	v_cndmask_b32_e64 v33, 0, v11, s[0:1]
	v_cmp_le_i32_e64 s[0:1], v0, v8
	v_cndmask_b32_e64 v13, v5, 0, vcc
	ds_write_b128 v36, v[30:33] offset:17680
	v_cndmask_b32_e64 v10, 0, v6, s[0:1]
	v_cmp_lt_i32_e64 s[0:1], v0, v8
	v_lshlrev_b32_e32 v0, 4, v40
	v_and_b32_e32 v0, 0xf0, v0
	v_cndmask_b32_e64 v11, 0, v7, s[0:1]
	v_cmp_le_i32_e64 s[0:1], v47, v8
	v_lshrrev_b32_e32 v46, 4, v40
	v_and_b32_e32 v2, 16, v2
	v_cndmask_b32_e64 v12, 0, v4, s[0:1]
	s_mul_i32 s0, s15, 0x2100
	s_mul_hi_u32 s1, s14, 0x2100
	s_add_i32 s1, s1, s0
	s_mul_i32 s0, s14, 0x2100
	s_add_u32 s2, s86, s0
	s_addc_u32 s1, s87, s1
	s_lshl_b32 s0, s13, 8
	s_add_u32 s2, s2, s0
	s_addc_u32 s3, s1, 0
	v_lshl_add_u64 v[34:35], s[2:3], 0, v[0:1]
	v_mad_i64_i32 v[4:5], s[2:3], v3, s4, v[34:35]
	global_load_dwordx4 v[4:7], v[4:5], off offset:2048
	v_add_u32_e32 v0, 0x100, v40
	v_ashrrev_i32_e32 v42, 4, v0
	ds_write_b128 v36, v[10:13] offset:17952
	v_mad_i64_i32 v[10:11], s[2:3], v42, s4, v[34:35]
	v_add_u32_e32 v0, 0x200, v40
	global_load_dwordx4 v[10:13], v[10:11], off offset:2048
	v_ashrrev_i32_e32 v43, 4, v0
	v_add_u32_e32 v0, 0x300, v40
	v_ashrrev_i32_e32 v44, 4, v0
	v_mad_i64_i32 v[30:31], s[2:3], v43, s4, v[34:35]
	v_mad_i64_i32 v[34:35], s[2:3], v44, s4, v[34:35]
	global_load_dwordx4 v[30:33], v[30:31], off offset:2048
	v_lshrrev_b32_e32 v0, 1, v9
	global_load_dwordx4 v[34:37], v[34:35], off offset:2048
	v_bitop3_b32 v45, v46, v0, 7 bitop3:0x6c
	v_lshlrev_b32_e32 v8, 8, v3
	v_lshlrev_b32_e32 v45, 5, v45
	v_or3_b32 v45, v45, v8, v2
	s_ashr_i32 s13, s12, 31
	s_lshl_b64 s[2:3], s[12:13], 15
	s_add_u32 s2, s84, s2
	s_addc_u32 s3, s85, s3
	s_mov_b32 s1, 0x800000
	s_waitcnt vmcnt(3)
	ds_write_b128 v45, v[4:7]
	v_bitop3_b32 v5, v42, v0, 7 bitop3:0x6c
	v_lshlrev_b32_e32 v4, 8, v42
	v_lshlrev_b32_e32 v5, 5, v5
	v_or3_b32 v46, v5, v4, v2
	v_bitop3_b32 v5, v43, v0, 7 bitop3:0x6c
	v_lshlrev_b32_e32 v4, 8, v43
	v_lshlrev_b32_e32 v5, 5, v5
	v_bitop3_b32 v0, v44, v0, 7 bitop3:0x6c
	s_waitcnt vmcnt(2)
; template <int QS>
; DI void pv_tile(const char* Vs, const f32x4 (&s)[4][QS], f32x4 (&o)[QS][8], int lane) {
;   const int g = lane >> 4, i = lane & 15;
; #pragma unroll
;   for (int c = 0; c < 2; ++c) {
;     bf16x8 pf[QS];
; #pragma unroll
;     for (int qs = 0; qs < QS; ++qs) {
;       union { uint4 u; bf16x8 v; } cv;
;       cv.u.x = pack2(s[2 * c][qs][0], s[2 * c][qs][1]); cv.u.y = pack2(s[2 * c][qs][2], s[2 * c][qs][3]);
;       cv.u.z = pack2(s[2 * c + 1][qs][0], s[2 * c + 1][qs][1]); cv.u.w = pack2(s[2 * c + 1][qs][2], s[2 * c + 1][qs][3]);
;       pf[qs] = cv.v;
;     }
;     const int r1 = 32 * c + 4 * g + (i >> 2), r2 = r1 + 16;
; #pragma unroll
;     for (int dt = 0; dt < 8; ++dt) {
;       const s16x4 lo = __builtin_amdgcn_ds_read_tr16_b64_v4i16(LDSP(s16x4, Vs + r1 * 256 + ((dt ^ (r1 & 7)) << 5) + 8 * (i & 3)));
;       const s16x4 hi = __builtin_amdgcn_ds_read_tr16_b64_v4i16(LDSP(s16x4, Vs + r2 * 256 + ((dt ^ (r2 & 7)) << 5) + 8 * (i & 3)));
;       bf16x8 vf; vf[0] = lo[0]; vf[1] = lo[1]; vf[2] = lo[2]; vf[3] = lo[3]; vf[4] = hi[0]; vf[5] = hi[1]; vf[6] = hi[2]; vf[7] = hi[3];
; #pragma unroll
;       for (int qs = 0; qs < QS; ++qs) o[qs][dt] = __builtin_amdgcn_mfma_f32_16x16x32_bf16(vf, pf[qs], o[qs][dt], 0, 0, 0);
; DI void gla_pass3(int item, const bf16_t* __restrict__ z, const float* __restrict__ w_up, const float* __restrict__ b_alpha,
;                   const float* __restrict__ Sbuf, const float* __restrict__ gw, bf16_t* __restrict__ mix, char* smem) {
;     ...
;   load_tile_v(tid, z + tok0 * ABP + ZV + h * 128, ABP, Vs);
;   {
;     const float* Sg = Sbuf + (size_t)item * 64 * 128;
; #pragma unroll
;     for (int i = 0; i < 4; ++i) {
;       const int idx = tid + 256 * i, row = idx >> 4, ch = idx & 15;
;       const f32x4 x0 = *(const f32x4*)(Sg + row * 128 + ch * 8), x1 = *(const f32x4*)(Sg + row * 128 + ch * 8 + 4);
;       u32x4 w; w[0] = pack2(x0[0], x0[1]); w[1] = pack2(x0[2], x0[3]); w[2] = pack2(x1[0], x1[1]); w[3] = pack2(x1[2], x1[3]);
;       *(u32x4*)(Ss + voff(row, ch)) = w;
;     }
;   }
;   __syncthreads();
;   f32x4 o[1][8];
; #pragma unroll
;   for (int dt = 0; dt < 8; ++dt) o[0][dt] = (f32x4){0.f, 0.f, 0.f, 0.f};
;   {
;     f32x4 sa[4][1];
; #pragma unroll
;     for (int kt = 0; kt < 4; ++kt) sa[kt][0] = *(const f32x4*)(kiT + iq * 68 + kt * 16 + 4 * g);
;     pv_tile<1>(Vs, sa, o, lane);
;     pv_tile<1>(Ss, sq, o, lane);
	ds_write_b128 v46, v[10:13]
	v_or3_b32 v12, v5, v4, v2
	v_lshlrev_b32_e32 v4, 8, v44
	v_lshlrev_b32_e32 v0, 5, v0
	v_or3_b32 v13, v0, v4, v2
	v_lshlrev_b32_e32 v0, 5, v9
	v_lshlrev_b32_e32 v2, 7, v3
	v_lshl_add_u64 v[10:11], s[2:3], 0, v[0:1]
	v_ashrrev_i32_e32 v3, 31, v2
	s_waitcnt vmcnt(1)
	ds_write_b128 v12, v[30:33]
	s_waitcnt vmcnt(0)
	ds_write_b128 v13, v[34:37]
	v_lshl_add_u64 v[6:7], v[2:3], 2, v[10:11]
	global_load_dwordx4 v[2:5], v[6:7], off offset:16
	s_nop 0
	global_load_dwordx4 v[6:9], v[6:7], off
	v_and_b32_e32 v0, 48, v40
	v_lshlrev_b32_e32 v31, 3, v39
	v_cvt_pk_bf16_f32 v36, v18, v19
	v_cvt_pk_bf16_f32 v37, v20, v21
	s_waitcnt vmcnt(0)
	v_cvt_pk_bf16_f32 v6, v6, v7
	v_cvt_pk_bf16_f32 v7, v8, v9
	v_cvt_pk_bf16_f32 v8, v2, v3
	v_lshlrev_b32_e32 v2, 7, v42
	v_ashrrev_i32_e32 v3, 31, v2
	v_cvt_pk_bf16_f32 v9, v4, v5
	ds_write_b128 v45, v[6:9] offset:34816
	v_lshl_add_u64 v[6:7], v[2:3], 2, v[10:11]
	global_load_dwordx4 v[2:5], v[6:7], off offset:16
	s_nop 0
	global_load_dwordx4 v[6:9], v[6:7], off
	s_waitcnt vmcnt(0)
	v_cvt_pk_bf16_f32 v6, v6, v7
	v_cvt_pk_bf16_f32 v7, v8, v9
	v_cvt_pk_bf16_f32 v8, v2, v3
	v_lshlrev_b32_e32 v2, 7, v43
	v_ashrrev_i32_e32 v3, 31, v2
	v_cvt_pk_bf16_f32 v9, v4, v5
	ds_write_b128 v46, v[6:9] offset:34816
	v_lshl_add_u64 v[6:7], v[2:3], 2, v[10:11]
	global_load_dwordx4 v[2:5], v[6:7], off offset:16
	s_nop 0
	global_load_dwordx4 v[6:9], v[6:7], off
	s_waitcnt vmcnt(0)
	v_cvt_pk_bf16_f32 v6, v6, v7
	v_cvt_pk_bf16_f32 v7, v8, v9
	v_cvt_pk_bf16_f32 v8, v2, v3
	v_lshlrev_b32_e32 v2, 7, v44
	v_ashrrev_i32_e32 v3, 31, v2
	v_cvt_pk_bf16_f32 v9, v4, v5
	ds_write_b128 v12, v[6:9] offset:34816
	v_lshl_add_u64 v[6:7], v[2:3], 2, v[10:11]
	global_load_dwordx4 v[2:5], v[6:7], off offset:16
	s_nop 0
	global_load_dwordx4 v[6:9], v[6:7], off
	v_mad_u64_u32 v[10:11], s[2:3], v38, s5, v[0:1]
	s_waitcnt vmcnt(0)
	v_cvt_pk_bf16_f32 v6, v6, v7
	v_cvt_pk_bf16_f32 v7, v8, v9
	v_cvt_pk_bf16_f32 v8, v2, v3
	v_cvt_pk_bf16_f32 v9, v4, v5
	v_lshlrev_b32_e32 v0, 6, v39
	ds_write_b128 v13, v[6:9] offset:34816
	s_waitcnt lgkmcnt(0)
	s_barrier
	ds_read_b128 v[2:5], v10 offset:17408
	ds_read_b128 v[6:9], v10 offset:17472
	ds_read_b128 v[32:35], v10 offset:17536
	ds_read_b128 v[46:49], v10 offset:17600
	v_and_b32_e32 v0, 0xf00, v0
	v_and_b32_e32 v10, 0xe0, v31
	v_and_or_b32 v0, v31, 24, v0
	v_or_b32_e32 v30, v0, v10
	s_waitcnt lgkmcnt(3)
	v_cvt_pk_bf16_f32 v2, v2, v3
	v_cvt_pk_bf16_f32 v3, v4, v5
	s_waitcnt lgkmcnt(2)
	v_cvt_pk_bf16_f32 v4, v6, v7
	v_cvt_pk_bf16_f32 v5, v8, v9
	ds_read_b64_tr_b16 v[6:7], v30
	ds_read_b64_tr_b16 v[8:9], v30 offset:4096
	s_waitcnt lgkmcnt(0)
	v_mfma_f32_16x16x32_bf16 v[50:53], v[6:9], v[2:5], 0
	v_bitop3_b32 v6, v31, 32, v200 bitop3:0x6c
	v_or_b32_e32 v45, v0, v6
	ds_read_b64_tr_b16 v[6:7], v45
	ds_read_b64_tr_b16 v[8:9], v45 offset:4096
	s_waitcnt lgkmcnt(0)
	v_mfma_f32_16x16x32_bf16 v[54:57], v[6:9], v[2:5], 0
	v_bitop3_b32 v6, v31, 64, v200 bitop3:0x6c
	v_or_b32_e32 v44, v0, v6
	ds_read_b64_tr_b16 v[6:7], v44
	ds_read_b64_tr_b16 v[8:9], v44 offset:4096
	s_waitcnt lgkmcnt(0)
	v_mfma_f32_16x16x32_bf16 v[58:61], v[6:9], v[2:5], 0
	v_bitop3_b32 v6, v31, s92, v200 bitop3:0x6c
	v_or_b32_e32 v43, v0, v6
	ds_read_b64_tr_b16 v[6:7], v43
	ds_read_b64_tr_b16 v[8:9], v43 offset:4096
	s_waitcnt lgkmcnt(0)
	v_mfma_f32_16x16x32_bf16 v[62:65], v[6:9], v[2:5], 0
	v_bitop3_b32 v6, v31, s95, v200 bitop3:0x6c
	v_or_b32_e32 v42, v0, v6
	ds_read_b64_tr_b16 v[6:7], v42
	ds_read_b64_tr_b16 v[8:9], v42 offset:4096
	s_waitcnt lgkmcnt(0)
	v_mfma_f32_16x16x32_bf16 v[66:69], v[6:9], v[2:5], 0
	v_bitop3_b32 v6, v31, s71, v200 bitop3:0x6c
	v_or_b32_e32 v40, v0, v6
	ds_read_b64_tr_b16 v[6:7], v40
	ds_read_b64_tr_b16 v[8:9], v40 offset:4096
	s_waitcnt lgkmcnt(0)
	v_mfma_f32_16x16x32_bf16 v[70:73], v[6:9], v[2:5], 0
	v_bitop3_b32 v6, v31, s68, v200 bitop3:0x6c
	v_or_b32_e32 v39, v0, v6
	ds_read_b64_tr_b16 v[6:7], v39
	ds_read_b64_tr_b16 v[8:9], v39 offset:4096
	s_waitcnt lgkmcnt(0)
	v_mfma_f32_16x16x32_bf16 v[10:13], v[6:9], v[2:5], 0
	v_bitop3_b32 v6, v31, s69, v31 bitop3:0xc
	v_or_b32_e32 v0, v0, v6
	ds_read_b64_tr_b16 v[6:7], v0
	ds_read_b64_tr_b16 v[8:9], v0 offset:4096
	s_waitcnt lgkmcnt(0)
	v_mfma_f32_16x16x32_bf16 v[2:5], v[6:9], v[2:5], 0
	v_cvt_pk_bf16_f32 v6, v32, v33
	v_cvt_pk_bf16_f32 v7, v34, v35
	ds_read_b64_tr_b16 v[32:33], v30 offset:8192
	ds_read_b64_tr_b16 v[34:35], v30 offset:12288
	v_cvt_pk_bf16_f32 v8, v46, v47
	v_cvt_pk_bf16_f32 v9, v48, v49
	ds_read_b64_tr_b16 v[46:47], v45 offset:8192
	ds_read_b64_tr_b16 v[48:49], v45 offset:12288
	s_waitcnt lgkmcnt(2)
	v_mfma_f32_16x16x32_bf16 v[32:35], v[32:35], v[6:9], v[50:53]
	s_nop 2
	ds_read_b64_tr_b16 v[50:51], v44 offset:8192
	ds_read_b64_tr_b16 v[52:53], v44 offset:12288
	s_waitcnt lgkmcnt(2)
	v_mfma_f32_16x16x32_bf16 v[46:49], v[46:49], v[6:9], v[54:57]
	s_nop 2
	ds_read_b64_tr_b16 v[54:55], v43 offset:8192
	ds_read_b64_tr_b16 v[56:57], v43 offset:12288
	s_waitcnt lgkmcnt(2)
	v_mfma_f32_16x16x32_bf16 v[50:53], v[50:53], v[6:9], v[58:61]
	s_nop 2
	ds_read_b64_tr_b16 v[58:59], v42 offset:8192
	ds_read_b64_tr_b16 v[60:61], v42 offset:12288
	s_waitcnt lgkmcnt(2)
	v_mfma_f32_16x16x32_bf16 v[54:57], v[54:57], v[6:9], v[62:65]
	s_nop 2
	ds_read_b64_tr_b16 v[62:63], v40 offset:8192
	ds_read_b64_tr_b16 v[64:65], v40 offset:12288
	s_waitcnt lgkmcnt(2)
	v_mfma_f32_16x16x32_bf16 v[58:61], v[58:61], v[6:9], v[66:69]
	s_nop 2
	ds_read_b64_tr_b16 v[66:67], v39 offset:8192
	ds_read_b64_tr_b16 v[68:69], v39 offset:12288
	s_waitcnt lgkmcnt(0)
	v_mfma_f32_16x16x32_bf16 v[10:13], v[66:69], v[6:9], v[10:13]
	ds_read_b64_tr_b16 v[66:67], v0 offset:8192
	ds_read_b64_tr_b16 v[68:69], v0 offset:12288
	v_mfma_f32_16x16x32_bf16 v[62:65], v[62:65], v[6:9], v[70:73]
	s_waitcnt lgkmcnt(0)
; DI void gla_pass3(int item, const bf16_t* __restrict__ z, const float* __restrict__ w_up, const float* __restrict__ b_alpha,
;                   const float* __restrict__ Sbuf, const float* __restrict__ gw, bf16_t* __restrict__ mix, char* smem) {
;     ...
;     pv_tile<1>(Vs, sa, o, lane);
;     pv_tile<1>(Ss, sq, o, lane);
;   }
;   {
;     float ssq = 0.f;
; #pragma unroll
;     for (int dt = 0; dt < 8; ++dt) ssq += (o[0][dt][0] * o[0][dt][0] + o[0][dt][1] * o[0][dt][1]) + (o[0][dt][2] * o[0][dt][2] + o[0][dt][3] * o[0][dt][3]);
;     ssq += __shfl_xor(ssq, 16); ssq += __shfl_xor(ssq, 32);
	v_mfma_f32_16x16x32_bf16 v[2:5], v[66:69], v[6:9], v[2:5]
	v_cvt_pk_bf16_f32 v6, v22, v23
	v_cvt_pk_bf16_f32 v7, v24, v25
	ds_read_b64_tr_b16 v[22:23], v30 offset:34816
	ds_read_b64_tr_b16 v[24:25], v30 offset:38912
	v_cvt_pk_bf16_f32 v8, v26, v27
	v_cvt_pk_bf16_f32 v9, v28, v29
	ds_read_b64_tr_b16 v[26:27], v45 offset:34816
	ds_read_b64_tr_b16 v[28:29], v45 offset:38912
	s_waitcnt lgkmcnt(2)
	v_mfma_f32_16x16x32_bf16 v[22:25], v[22:25], v[6:9], v[32:35]
	s_nop 2
	ds_read_b64_tr_b16 v[32:33], v44 offset:34816
	ds_read_b64_tr_b16 v[34:35], v44 offset:38912
	s_waitcnt lgkmcnt(2)
	v_mfma_f32_16x16x32_bf16 v[26:29], v[26:29], v[6:9], v[46:49]
	s_waitcnt lgkmcnt(0)
	v_mfma_f32_16x16x32_bf16 v[46:49], v[32:35], v[6:9], v[50:53]
	ds_read_b64_tr_b16 v[32:33], v43 offset:34816
	ds_read_b64_tr_b16 v[34:35], v43 offset:38912
	s_waitcnt lgkmcnt(0)
	v_mfma_f32_16x16x32_bf16 v[50:53], v[32:35], v[6:9], v[54:57]
	ds_read_b64_tr_b16 v[32:33], v42 offset:34816
	ds_read_b64_tr_b16 v[34:35], v42 offset:38912
	s_waitcnt lgkmcnt(0)
	v_mfma_f32_16x16x32_bf16 v[54:57], v[32:35], v[6:9], v[58:61]
	ds_read_b64_tr_b16 v[32:33], v40 offset:34816
	ds_read_b64_tr_b16 v[34:35], v40 offset:38912
	s_waitcnt lgkmcnt(0)
	v_mfma_f32_16x16x32_bf16 v[58:61], v[32:35], v[6:9], v[62:65]
	ds_read_b64_tr_b16 v[32:33], v39 offset:34816
	ds_read_b64_tr_b16 v[34:35], v39 offset:38912
	s_waitcnt lgkmcnt(0)
	v_mfma_f32_16x16x32_bf16 v[62:65], v[32:35], v[6:9], v[10:13]
	s_nop 2
	ds_read_b64_tr_b16 v[10:11], v0 offset:34816
	ds_read_b64_tr_b16 v[12:13], v0 offset:38912
	v_cvt_pk_bf16_f32 v34, v14, v15
	v_cvt_pk_bf16_f32 v35, v16, v17
	s_waitcnt lgkmcnt(0)
	v_mfma_f32_16x16x32_bf16 v[2:5], v[10:13], v[6:9], v[2:5]
	ds_read_b64_tr_b16 v[6:7], v30 offset:43008
	ds_read_b64_tr_b16 v[8:9], v30 offset:47104
	s_waitcnt lgkmcnt(0)
	v_mfma_f32_16x16x32_bf16 v[30:33], v[6:9], v[34:37], v[22:25]
	ds_read_b64_tr_b16 v[6:7], v45 offset:43008
	ds_read_b64_tr_b16 v[8:9], v45 offset:47104
	s_waitcnt lgkmcnt(0)
	v_mfma_f32_16x16x32_bf16 v[26:29], v[6:9], v[34:37], v[26:29]
	ds_read_b64_tr_b16 v[6:7], v44 offset:43008
	ds_read_b64_tr_b16 v[8:9], v44 offset:47104
	s_waitcnt lgkmcnt(0)
	v_mfma_f32_16x16x32_bf16 v[22:25], v[6:9], v[34:37], v[46:49]
	ds_read_b64_tr_b16 v[6:7], v43 offset:43008
	ds_read_b64_tr_b16 v[8:9], v43 offset:47104
	s_waitcnt lgkmcnt(0)
	v_mfma_f32_16x16x32_bf16 v[18:21], v[6:9], v[34:37], v[50:53]
	ds_read_b64_tr_b16 v[6:7], v42 offset:43008
	ds_read_b64_tr_b16 v[8:9], v42 offset:47104
	s_waitcnt lgkmcnt(0)
	v_mfma_f32_16x16x32_bf16 v[14:17], v[6:9], v[34:37], v[54:57]
	ds_read_b64_tr_b16 v[6:7], v40 offset:43008
	ds_read_b64_tr_b16 v[8:9], v40 offset:47104
	s_waitcnt lgkmcnt(0)
	v_mfma_f32_16x16x32_bf16 v[10:13], v[6:9], v[34:37], v[58:61]
	ds_read_b64_tr_b16 v[6:7], v39 offset:43008
	ds_read_b64_tr_b16 v[8:9], v39 offset:47104
	ds_read_b64_tr_b16 v[42:43], v0 offset:43008
	ds_read_b64_tr_b16 v[44:45], v0 offset:47104
	v_mul_f32_e32 v0, v14, v14
	s_waitcnt lgkmcnt(2)
	v_mfma_f32_16x16x32_bf16 v[6:9], v[6:9], v[34:37], v[62:65]
	v_mul_f32_e32 v39, v15, v15
	v_mul_f32_e32 v40, v16, v16
	s_waitcnt lgkmcnt(0)
	v_mfma_f32_16x16x32_bf16 v[2:5], v[42:45], v[34:37], v[2:5]
	v_mov_b32_e32 v36, v31
	v_mov_b32_e32 v37, v27
	v_mov_b32_e32 v34, v30
	v_mov_b32_e32 v35, v26
	v_pk_mul_f32 v[36:37], v[36:37], v[36:37]
	v_mov_b32_e32 v42, v33
	v_mov_b32_e32 v43, v29
	v_pk_fma_f32 v[34:35], v[34:35], v[34:35], v[36:37]
	v_mov_b32_e32 v36, v32
	v_mov_b32_e32 v37, v28
	v_pk_mul_f32 v[42:43], v[42:43], v[42:43]
	s_nop 0
	v_pk_fma_f32 v[36:37], v[36:37], v[36:37], v[42:43]
	v_pk_mul_f32 v[42:43], v[22:23], v[22:23]
	v_pk_add_f32 v[34:35], v[34:35], v[36:37]
	v_pk_mul_f32 v[36:37], v[24:25], v[24:25]
	v_pk_add_f32 v[34:35], v[34:35], v[34:35] op_sel:[0,1] op_sel_hi:[1,0]
	v_pk_mov_b32 v[44:45], v[42:43], v[36:37] op_sel:[1,0]
	v_mov_b32_e32 v43, v37
	v_pk_add_f32 v[36:37], v[44:45], v[42:43]
	v_mov_b32_e32 v35, v0
	v_pk_add_f32 v[36:37], v[36:37], v[36:37] op_sel:[0,1] op_sel_hi:[1,0]
	v_mul_f32_e32 v0, v19, v19
	v_mov_b32_e32 v37, v39
	v_pk_add_f32 v[34:35], v[34:35], v[36:37]
	v_pk_fma_f32 v[36:37], v[18:19], v[18:19], v[0:1] op_sel_hi:[1,1,0]
	v_mul_f32_e32 v0, v21, v21
	v_mul_f32_e32 v44, v17, v17
	v_pk_fma_f32 v[42:43], v[20:21], v[20:21], v[0:1] op_sel_hi:[1,1,0]
	v_mov_b32_e32 v37, v40
	v_mov_b32_e32 v43, v44
	v_pk_add_f32 v[36:37], v[36:37], v[42:43]
	v_pk_mul_f32 v[42:43], v[10:11], v[10:11]
	v_pk_add_f32 v[34:35], v[34:35], v[36:37]
	v_pk_mul_f32 v[36:37], v[12:13], v[12:13]
	v_mul_f32_e32 v0, v2, v2
	v_pk_mov_b32 v[44:45], v[42:43], v[36:37] op_sel:[1,0]
	v_mov_b32_e32 v43, v37
	v_pk_add_f32 v[36:37], v[44:45], v[42:43]
	v_mul_f32_e32 v39, v3, v3
	v_pk_add_f32 v[34:35], v[34:35], v[34:35] op_sel:[0,1] op_sel_hi:[1,0]
	v_pk_add_f32 v[36:37], v[36:37], v[36:37] op_sel:[0,1] op_sel_hi:[1,0]
	v_mov_b32_e32 v35, v0
	v_mov_b32_e32 v37, v39
	v_mul_f32_e32 v0, v7, v7
	v_pk_add_f32 v[34:35], v[34:35], v[36:37]
	v_pk_fma_f32 v[36:37], v[6:7], v[6:7], v[0:1] op_sel_hi:[1,1,0]
	v_mul_f32_e32 v0, v9, v9
	v_mul_f32_e32 v40, v4, v4
	v_mul_f32_e32 v44, v5, v5
	v_pk_fma_f32 v[42:43], v[8:9], v[8:9], v[0:1] op_sel_hi:[1,1,0]
	v_mov_b32_e32 v37, v40
	v_mov_b32_e32 v43, v44
	v_pk_add_f32 v[36:37], v[36:37], v[42:43]
	v_ashrrev_i32_e32 v39, 31, v38
	v_pk_add_f32 v[34:35], v[34:35], v[36:37]
	v_lshl_add_u64 v[36:37], s[14:15], 0, v[38:39]
	v_add_f32_e32 v0, v34, v35
	v_and_b32_e32 v35, 64, v198
	v_xor_b32_e32 v34, 16, v198
	v_add_u32_e32 v35, 64, v35
	v_cmp_lt_i32_e32 vcc, v34, v35
	s_nop 1
	v_cndmask_b32_e32 v34, v198, v34, vcc
	v_lshlrev_b32_e32 v34, 2, v34
	ds_bpermute_b32 v34, v34, v0
	s_waitcnt lgkmcnt(0)
; DI unsigned pack2(float lo, float hi) { unsigned r; asm("v_cvt_pk_bf16_f32 %0, %1, %2" : "=v"(r) : "v"(lo), "v"(hi)); return r; }
; DI float lo2f(unsigned u) { return __uint_as_float(u << 16); }
; DI float hi2f(unsigned u) { return __uint_as_float(u & 0xffff0000u); }
; DI float sigmoidf_(float x) { return 1.f / (1.f + __expf(-x)); }
; DI void gla_pass3(int item, const bf16_t* __restrict__ z, const float* __restrict__ w_up, const float* __restrict__ b_alpha,
;                   const float* __restrict__ Sbuf, const float* __restrict__ gw, bf16_t* __restrict__ mix, char* smem) {
;     ...
;     ssq += __shfl_xor(ssq, 16); ssq += __shfl_xor(ssq, 32);
;     const float r = rsqrtf(ssq * (1.f / 128.f) + 1e-6f);
; #pragma unroll
;     for (int dt = 0; dt < 8; ++dt) {
;       const int dv = dt * 16 + 4 * g, col = h * 128 + dv;
;       const u32x2 gq = *(const u32x2*)(z + (tok0 + iq) * ABP + ZG + col);
;       const float gg[4] = {lo2f(gq[0]), hi2f(gq[0]), lo2f(gq[1]), hi2f(gq[1])};
;       const f32x4 w = *(const f32x4*)(gw + dv);
;       float y[4];
; #pragma unroll
;       for (int e = 0; e < 4; ++e) y[e] = o[0][dt][e] * r * w[e] * (gg[e] * sigmoidf_(gg[e]));
;       u32x2 ov; ov[0] = pack2(y[0], y[1]); ov[1] = pack2(y[2], y[3]);
;       *(u32x2*)(mix + (tok0 + iq) * DM + col) = ov;
;     }
	v_add_f32_e32 v0, v0, v34
	v_xor_b32_e32 v34, 32, v198
	v_cmp_lt_i32_e32 vcc, v34, v35
	s_nop 1
	v_cndmask_b32_e32 v34, v198, v34, vcc
	v_lshlrev_b32_e32 v34, 2, v34
	ds_bpermute_b32 v34, v34, v0
	s_waitcnt lgkmcnt(0)
	v_add_f32_e32 v0, v0, v34
	v_fmamk_f32 v0, v0, 0x3c000000, v191
	v_cmp_gt_f32_e32 vcc, s1, v0
	v_mul_f32_e32 v34, 0x4b800000, v0
	s_nop 0
	v_cndmask_b32_e32 v0, v0, v34, vcc
	v_rsq_f32_e32 v0, v0
	s_nop 0
	v_mul_f32_e32 v34, 0x45800000, v0
	v_cndmask_b32_e32 v40, v0, v34, vcc
	v_mov_b64_e32 v[34:35], s[86:87]
	v_mad_u64_u32 v[34:35], s[2:3], v36, s4, v[34:35]
	v_mov_b32_e32 v0, v35
	v_mad_u64_u32 v[38:39], s[2:3], v37, s4, v[0:1]
	v_mov_b32_e32 v35, v38
	s_mov_b64 s[2:3], 0x1000
	v_lshl_add_u64 v[34:35], v[34:35], 0, s[2:3]
	v_lshl_or_b32 v0, v41, 1, s0
	v_lshl_add_u64 v[38:39], v[34:35], 0, v[0:1]
	global_load_dwordx2 v[38:39], v[38:39], off
	v_mul_f32_e32 v30, v30, v40
	v_mul_f32_e32 v31, v31, v40
	v_mul_f32_e32 v32, v32, v40
	v_readlane_b32 s2, v251, 32
	v_lshlrev_b64 v[36:37], 12, v[36:37]
	v_readlane_b32 s3, v251, 33
	v_mul_f32_e32 v26, v26, v40
	v_mul_f32_e32 v27, v27, v40
	v_lshl_add_u64 v[36:37], s[2:3], 0, v[36:37]
	v_mul_f32_e32 v28, v28, v40
	v_mul_f32_e32 v29, v29, v40
	v_mul_f32_e32 v22, v22, v40
	v_mul_f32_e32 v23, v23, v40
	v_mul_f32_e32 v24, v24, v40
	v_mul_f32_e32 v25, v25, v40
	v_mul_f32_e32 v18, v18, v40
	v_mul_f32_e32 v19, v19, v40
	v_mul_f32_e32 v20, v20, v40
	v_mul_f32_e32 v21, v21, v40
	v_mul_f32_e32 v14, v14, v40
	v_mul_f32_e32 v15, v15, v40
	v_mul_f32_e32 v16, v16, v40
	v_mul_f32_e32 v17, v17, v40
	v_mul_f32_e32 v10, v10, v40
	v_mul_f32_e32 v11, v11, v40
	v_mul_f32_e32 v12, v12, v40
	v_mul_f32_e32 v13, v13, v40
	v_mul_f32_e32 v6, v6, v40
	v_mul_f32_e32 v7, v7, v40
	v_mul_f32_e32 v8, v8, v40
	v_mul_f32_e32 v9, v9, v40
	v_mul_f32_e32 v2, v2, v40
	v_mul_f32_e32 v3, v3, v40
	v_mul_f32_e32 v4, v4, v40
	v_mul_f32_e32 v5, v5, v40
	s_waitcnt vmcnt(0)
	v_lshlrev_b32_e32 v46, 16, v38
	v_and_b32_e32 v47, 0xffff0000, v38
	v_lshlrev_b32_e32 v38, 2, v41
	global_load_dwordx4 v[42:45], v38, s[10:11]
	v_mul_f32_e32 v41, 0xbfb8aa3b, v46
	v_exp_f32_e32 v41, v41
	v_lshlrev_b32_e32 v48, 16, v39
	v_and_b32_e32 v39, 0xffff0000, v39
	v_add_f32_e32 v41, 1.0, v41
	s_waitcnt vmcnt(0)
	v_mul_f32_e32 v30, v42, v30
	v_div_scale_f32 v42, s[0:1], v41, v41, 1.0
	v_rcp_f32_e32 v49, v42
	v_mul_f32_e32 v31, v43, v31
	v_mul_f32_e32 v32, v44, v32
	v_fma_f32 v50, -v42, v49, 1.0
	v_fmac_f32_e32 v49, v50, v49
	v_div_scale_f32 v50, vcc, 1.0, v41, 1.0
	v_mul_f32_e32 v51, v50, v49
	v_fma_f32 v52, -v42, v51, v50
	v_fmac_f32_e32 v51, v52, v49
	v_fma_f32 v42, -v42, v51, v50
	v_div_fmas_f32 v42, v42, v49, v51
	v_div_fixup_f32 v41, v42, v41, 1.0
	v_mul_f32_e32 v41, v41, v46
	v_mul_f32_e32 v30, v41, v30
	v_mul_f32_e32 v41, 0xbfb8aa3b, v47
	v_exp_f32_e32 v41, v41
	s_nop 0
	v_add_f32_e32 v41, 1.0, v41
	v_div_scale_f32 v42, s[0:1], v41, v41, 1.0
	v_rcp_f32_e32 v43, v42
	s_nop 0
	v_fma_f32 v46, -v42, v43, 1.0
	v_fmac_f32_e32 v43, v46, v43
	v_div_scale_f32 v46, vcc, 1.0, v41, 1.0
	v_mul_f32_e32 v49, v46, v43
	v_fma_f32 v50, -v42, v49, v46
	v_fmac_f32_e32 v49, v50, v43
	v_fma_f32 v42, -v42, v49, v46
	v_div_fmas_f32 v42, v42, v43, v49
	v_div_fixup_f32 v41, v42, v41, 1.0
	v_mul_f32_e32 v41, v41, v47
	v_mul_f32_e32 v31, v41, v31
	v_mul_f32_e32 v41, 0xbfb8aa3b, v48
	v_exp_f32_e32 v41, v41
	s_nop 0
	v_add_f32_e32 v41, 1.0, v41
	v_div_scale_f32 v42, s[0:1], v41, v41, 1.0
	v_rcp_f32_e32 v43, v42
	s_nop 0
	v_fma_f32 v44, -v42, v43, 1.0
	v_fmac_f32_e32 v43, v44, v43
	v_div_scale_f32 v44, vcc, 1.0, v41, 1.0
	v_mul_f32_e32 v46, v44, v43
	v_fma_f32 v47, -v42, v46, v44
	v_fmac_f32_e32 v46, v47, v43
	v_fma_f32 v42, -v42, v46, v44
	v_div_fmas_f32 v42, v42, v43, v46
	v_div_fixup_f32 v41, v42, v41, 1.0
	v_mul_f32_e32 v41, v41, v48
	v_mul_f32_e32 v41, v41, v32
	v_mul_f32_e32 v32, v33, v40
	v_mul_f32_e32 v33, 0xbfb8aa3b, v39
	v_exp_f32_e32 v33, v33
	v_mul_f32_e32 v32, v45, v32
	v_add_f32_e32 v33, 1.0, v33
	v_div_scale_f32 v42, s[0:1], v33, v33, 1.0
	v_rcp_f32_e32 v43, v42
	s_nop 0
	v_fma_f32 v44, -v42, v43, 1.0
	v_fmac_f32_e32 v43, v44, v43
	v_div_scale_f32 v44, vcc, 1.0, v33, 1.0
	v_mul_f32_e32 v45, v44, v43
	v_fma_f32 v46, -v42, v45, v44
	v_fmac_f32_e32 v45, v46, v43
	v_fma_f32 v42, -v42, v45, v44
	v_div_fmas_f32 v42, v42, v43, v45
	v_div_fixup_f32 v33, v42, v33, 1.0
	v_mul_f32_e32 v33, v33, v39
	v_mul_f32_e32 v33, v33, v32
	v_cvt_pk_bf16_f32 v32, v30, v31
	v_cvt_pk_bf16_f32 v33, v41, v33
	v_lshl_add_u64 v[30:31], v[36:37], 0, v[0:1]
	global_store_dwordx2 v[30:31], v[32:33], off
	v_or_b32_e32 v32, 32, v0
	v_mov_b32_e32 v33, v1
	v_lshl_add_u64 v[32:33], v[34:35], 0, v[32:33]
	global_load_dwordx2 v[32:33], v[32:33], off
	s_waitcnt vmcnt(0)
	v_lshlrev_b32_e32 v36, 16, v32
	global_load_dwordx4 v[42:45], v38, s[10:11] offset:64
	v_mul_f32_e32 v39, 0xbfb8aa3b, v36
	v_exp_f32_e32 v39, v39
	v_and_b32_e32 v32, 0xffff0000, v32
	v_lshlrev_b32_e32 v37, 16, v33
	v_and_b32_e32 v33, 0xffff0000, v33
	v_add_f32_e32 v39, 1.0, v39
	v_div_scale_f32 v41, s[0:1], v39, v39, 1.0
	s_waitcnt vmcnt(0)
; DI unsigned pack2(float lo, float hi) { unsigned r; asm("v_cvt_pk_bf16_f32 %0, %1, %2" : "=v"(r) : "v"(lo), "v"(hi)); return r; }
; DI float lo2f(unsigned u) { return __uint_as_float(u << 16); }
; DI float hi2f(unsigned u) { return __uint_as_float(u & 0xffff0000u); }
; DI float sigmoidf_(float x) { return 1.f / (1.f + __expf(-x)); }
; DI void gla_pass3(int item, const bf16_t* __restrict__ z, const float* __restrict__ w_up, const float* __restrict__ b_alpha,
;                   const float* __restrict__ Sbuf, const float* __restrict__ gw, bf16_t* __restrict__ mix, char* smem) {
;     ...
;     for (int dt = 0; dt < 8; ++dt) {
;       const int dv = dt * 16 + 4 * g, col = h * 128 + dv;
;       const u32x2 gq = *(const u32x2*)(z + (tok0 + iq) * ABP + ZG + col);
;       const float gg[4] = {lo2f(gq[0]), hi2f(gq[0]), lo2f(gq[1]), hi2f(gq[1])};
;       const f32x4 w = *(const f32x4*)(gw + dv);
;       float y[4];
; #pragma unroll
;       for (int e = 0; e < 4; ++e) y[e] = o[0][dt][e] * r * w[e] * (gg[e] * sigmoidf_(gg[e]));
;       u32x2 ov; ov[0] = pack2(y[0], y[1]); ov[1] = pack2(y[2], y[3]);
;       *(u32x2*)(mix + (tok0 + iq) * DM + col) = ov;
;     }
	v_mul_f32_e32 v26, v42, v26
	v_rcp_f32_e32 v42, v41
	v_mul_f32_e32 v27, v43, v27
	v_mul_f32_e32 v28, v44, v28
	v_mul_f32_e32 v29, v45, v29
	v_fma_f32 v46, -v41, v42, 1.0
	v_fmac_f32_e32 v42, v46, v42
	v_div_scale_f32 v46, vcc, 1.0, v39, 1.0
	v_mul_f32_e32 v47, v46, v42
	v_fma_f32 v48, -v41, v47, v46
	v_fmac_f32_e32 v47, v48, v42
	v_fma_f32 v41, -v41, v47, v46
	v_div_fmas_f32 v41, v41, v42, v47
	v_div_fixup_f32 v39, v41, v39, 1.0
	v_mul_f32_e32 v36, v39, v36
	v_mul_f32_e32 v26, v26, v36
	v_mul_f32_e32 v36, 0xbfb8aa3b, v32
	v_exp_f32_e32 v36, v36
	s_nop 0
	v_add_f32_e32 v36, 1.0, v36
	v_div_scale_f32 v39, s[0:1], v36, v36, 1.0
	v_rcp_f32_e32 v41, v39
	s_nop 0
	v_fma_f32 v42, -v39, v41, 1.0
	v_fmac_f32_e32 v41, v42, v41
	v_div_scale_f32 v42, vcc, 1.0, v36, 1.0
	v_mul_f32_e32 v43, v42, v41
	v_fma_f32 v46, -v39, v43, v42
	v_fmac_f32_e32 v43, v46, v41
	v_fma_f32 v39, -v39, v43, v42
	v_div_fmas_f32 v39, v39, v41, v43
	v_div_fixup_f32 v36, v39, v36, 1.0
	v_mul_f32_e32 v32, v36, v32
	v_mul_f32_e32 v27, v27, v32
	v_mul_f32_e32 v32, 0xbfb8aa3b, v37
	v_exp_f32_e32 v32, v32
	v_cvt_pk_bf16_f32 v26, v26, v27
	s_nop 0
	v_add_f32_e32 v32, 1.0, v32
	v_div_scale_f32 v36, s[0:1], v32, v32, 1.0
	v_rcp_f32_e32 v39, v36
	s_nop 0
	v_fma_f32 v41, -v36, v39, 1.0
	v_fmac_f32_e32 v39, v41, v39
	v_div_scale_f32 v41, vcc, 1.0, v32, 1.0
	v_mul_f32_e32 v42, v41, v39
	v_fma_f32 v43, -v36, v42, v41
	v_fmac_f32_e32 v42, v43, v39
	v_fma_f32 v36, -v36, v42, v41
	v_div_fmas_f32 v36, v36, v39, v42
	v_div_fixup_f32 v32, v36, v32, 1.0
	v_mul_f32_e32 v32, v32, v37
	v_mul_f32_e32 v28, v28, v32
	v_mul_f32_e32 v32, 0xbfb8aa3b, v33
	v_exp_f32_e32 v32, v32
	s_nop 0
	v_add_f32_e32 v32, 1.0, v32
	v_div_scale_f32 v36, s[0:1], v32, v32, 1.0
	v_rcp_f32_e32 v37, v36
	s_nop 0
	v_fma_f32 v39, -v36, v37, 1.0
	v_fmac_f32_e32 v37, v39, v37
	v_div_scale_f32 v39, vcc, 1.0, v32, 1.0
	v_mul_f32_e32 v41, v39, v37
	v_fma_f32 v42, -v36, v41, v39
	v_fmac_f32_e32 v41, v42, v37
	v_fma_f32 v36, -v36, v41, v39
	v_div_fmas_f32 v36, v36, v37, v41
	v_div_fixup_f32 v32, v36, v32, 1.0
	v_mul_f32_e32 v32, v32, v33
	v_mul_f32_e32 v29, v29, v32
	v_cvt_pk_bf16_f32 v27, v28, v29
	global_store_dwordx2 v[30:31], v[26:27], off offset:32
	v_or_b32_e32 v26, 64, v0
	v_mov_b32_e32 v27, v1
	v_lshl_add_u64 v[26:27], v[34:35], 0, v[26:27]
	global_load_dwordx2 v[26:27], v[26:27], off
	s_waitcnt vmcnt(0)
	v_lshlrev_b32_e32 v32, 16, v26
	v_and_b32_e32 v33, 0xffff0000, v26
	v_lshlrev_b32_e32 v36, 16, v27
	v_and_b32_e32 v37, 0xffff0000, v27
	global_load_dwordx4 v[26:29], v38, s[10:11] offset:128
	s_waitcnt vmcnt(0)
	v_mul_f32_e32 v22, v22, v26
	v_mul_f32_e32 v26, 0xbfb8aa3b, v32
	v_exp_f32_e32 v26, v26
	v_mul_f32_e32 v23, v23, v27
	v_mul_f32_e32 v24, v24, v28
	v_mul_f32_e32 v25, v25, v29
	v_add_f32_e32 v26, 1.0, v26
	v_div_scale_f32 v39, s[0:1], v26, v26, 1.0
	v_rcp_f32_e32 v41, v39
	s_nop 0
	v_fma_f32 v42, -v39, v41, 1.0
	v_fmac_f32_e32 v41, v42, v41
	v_div_scale_f32 v42, vcc, 1.0, v26, 1.0
	v_mul_f32_e32 v43, v42, v41
	v_fma_f32 v44, -v39, v43, v42
	v_fmac_f32_e32 v43, v44, v41
	v_fma_f32 v39, -v39, v43, v42
	v_div_fmas_f32 v39, v39, v41, v43
	v_div_fixup_f32 v26, v39, v26, 1.0
	v_mul_f32_e32 v26, v26, v32
	v_mul_f32_e32 v22, v22, v26
	v_mul_f32_e32 v26, 0xbfb8aa3b, v33
	v_exp_f32_e32 v26, v26
	s_nop 0
	v_add_f32_e32 v26, 1.0, v26
	v_div_scale_f32 v27, s[0:1], v26, v26, 1.0
	v_rcp_f32_e32 v32, v27
	s_nop 0
	v_fma_f32 v39, -v27, v32, 1.0
	v_fmac_f32_e32 v32, v39, v32
	v_div_scale_f32 v39, vcc, 1.0, v26, 1.0
	v_mul_f32_e32 v41, v39, v32
	v_fma_f32 v42, -v27, v41, v39
	v_fmac_f32_e32 v41, v42, v32
	v_fma_f32 v27, -v27, v41, v39
	v_div_fmas_f32 v27, v27, v32, v41
	v_div_fixup_f32 v26, v27, v26, 1.0
	v_mul_f32_e32 v26, v26, v33
	v_mul_f32_e32 v23, v23, v26
	v_mul_f32_e32 v26, 0xbfb8aa3b, v36
	v_exp_f32_e32 v26, v26
	v_cvt_pk_bf16_f32 v22, v22, v23
	s_nop 0
	v_add_f32_e32 v26, 1.0, v26
	v_div_scale_f32 v27, s[0:1], v26, v26, 1.0
	v_rcp_f32_e32 v28, v27
	s_nop 0
	v_fma_f32 v32, -v27, v28, 1.0
	v_fmac_f32_e32 v28, v32, v28
	v_div_scale_f32 v32, vcc, 1.0, v26, 1.0
	v_mul_f32_e32 v33, v32, v28
	v_fma_f32 v39, -v27, v33, v32
	v_fmac_f32_e32 v33, v39, v28
	v_fma_f32 v27, -v27, v33, v32
	v_div_fmas_f32 v27, v27, v28, v33
	v_div_fixup_f32 v26, v27, v26, 1.0
	v_mul_f32_e32 v26, v26, v36
	v_mul_f32_e32 v24, v24, v26
	v_mul_f32_e32 v26, 0xbfb8aa3b, v37
	v_exp_f32_e32 v26, v26
	s_nop 0
	v_add_f32_e32 v26, 1.0, v26
	v_div_scale_f32 v27, s[0:1], v26, v26, 1.0
	v_rcp_f32_e32 v28, v27
	s_nop 0
	v_fma_f32 v29, -v27, v28, 1.0
	v_fmac_f32_e32 v28, v29, v28
	v_div_scale_f32 v29, vcc, 1.0, v26, 1.0
	v_mul_f32_e32 v32, v29, v28
	v_fma_f32 v33, -v27, v32, v29
	v_fmac_f32_e32 v32, v33, v28
	v_fma_f32 v27, -v27, v32, v29
	v_div_fmas_f32 v27, v27, v28, v32
	v_div_fixup_f32 v26, v27, v26, 1.0
	v_mul_f32_e32 v26, v26, v37
	v_mul_f32_e32 v25, v25, v26
	v_cvt_pk_bf16_f32 v23, v24, v25
	global_store_dwordx2 v[30:31], v[22:23], off offset:64
	v_or_b32_e32 v22, 0x60, v0
	v_mov_b32_e32 v23, v1
	v_lshl_add_u64 v[22:23], v[34:35], 0, v[22:23]
	global_load_dwordx2 v[22:23], v[22:23], off
	s_waitcnt vmcnt(0)
	v_lshlrev_b32_e32 v26, 16, v22
	v_and_b32_e32 v27, 0xffff0000, v22
	v_lshlrev_b32_e32 v28, 16, v23
	v_and_b32_e32 v29, 0xffff0000, v23
	global_load_dwordx4 v[22:25], v38, s[10:11] offset:192
	s_waitcnt vmcnt(0)
; DI unsigned pack2(float lo, float hi) { unsigned r; asm("v_cvt_pk_bf16_f32 %0, %1, %2" : "=v"(r) : "v"(lo), "v"(hi)); return r; }
; DI float lo2f(unsigned u) { return __uint_as_float(u << 16); }
; DI float hi2f(unsigned u) { return __uint_as_float(u & 0xffff0000u); }
; DI float sigmoidf_(float x) { return 1.f / (1.f + __expf(-x)); }
; DI void gla_pass3(int item, const bf16_t* __restrict__ z, const float* __restrict__ w_up, const float* __restrict__ b_alpha,
;                   const float* __restrict__ Sbuf, const float* __restrict__ gw, bf16_t* __restrict__ mix, char* smem) {
;     ...
;     for (int dt = 0; dt < 8; ++dt) {
;       const int dv = dt * 16 + 4 * g, col = h * 128 + dv;
;       const u32x2 gq = *(const u32x2*)(z + (tok0 + iq) * ABP + ZG + col);
;       const float gg[4] = {lo2f(gq[0]), hi2f(gq[0]), lo2f(gq[1]), hi2f(gq[1])};
;       const f32x4 w = *(const f32x4*)(gw + dv);
;       float y[4];
; #pragma unroll
;       for (int e = 0; e < 4; ++e) y[e] = o[0][dt][e] * r * w[e] * (gg[e] * sigmoidf_(gg[e]));
;       u32x2 ov; ov[0] = pack2(y[0], y[1]); ov[1] = pack2(y[2], y[3]);
;       *(u32x2*)(mix + (tok0 + iq) * DM + col) = ov;
;     }
	v_mul_f32_e32 v18, v18, v22
	v_mul_f32_e32 v22, 0xbfb8aa3b, v26
	v_exp_f32_e32 v22, v22
	v_mul_f32_e32 v19, v19, v23
	v_mul_f32_e32 v20, v20, v24
	v_mul_f32_e32 v21, v21, v25
	v_add_f32_e32 v22, 1.0, v22
	v_div_scale_f32 v32, s[0:1], v22, v22, 1.0
	v_rcp_f32_e32 v33, v32
	s_nop 0
	v_fma_f32 v36, -v32, v33, 1.0
	v_fmac_f32_e32 v33, v36, v33
	v_div_scale_f32 v36, vcc, 1.0, v22, 1.0
	v_mul_f32_e32 v37, v36, v33
	v_fma_f32 v39, -v32, v37, v36
	v_fmac_f32_e32 v37, v39, v33
	v_fma_f32 v32, -v32, v37, v36
	v_div_fmas_f32 v32, v32, v33, v37
	v_div_fixup_f32 v22, v32, v22, 1.0
	v_mul_f32_e32 v22, v22, v26
	v_mul_f32_e32 v18, v18, v22
	v_mul_f32_e32 v22, 0xbfb8aa3b, v27
	v_exp_f32_e32 v22, v22
	s_nop 0
	v_add_f32_e32 v22, 1.0, v22
	v_div_scale_f32 v23, s[0:1], v22, v22, 1.0
	v_rcp_f32_e32 v26, v23
	s_nop 0
	v_fma_f32 v32, -v23, v26, 1.0
	v_fmac_f32_e32 v26, v32, v26
	v_div_scale_f32 v32, vcc, 1.0, v22, 1.0
	v_mul_f32_e32 v33, v32, v26
	v_fma_f32 v36, -v23, v33, v32
	v_fmac_f32_e32 v33, v36, v26
	v_fma_f32 v23, -v23, v33, v32
	v_div_fmas_f32 v23, v23, v26, v33
	v_div_fixup_f32 v22, v23, v22, 1.0
	v_mul_f32_e32 v22, v22, v27
	v_mul_f32_e32 v19, v19, v22
	v_mul_f32_e32 v22, 0xbfb8aa3b, v28
	v_exp_f32_e32 v22, v22
	v_cvt_pk_bf16_f32 v18, v18, v19
	s_nop 0
	v_add_f32_e32 v22, 1.0, v22
	v_div_scale_f32 v23, s[0:1], v22, v22, 1.0
	v_rcp_f32_e32 v24, v23
	s_nop 0
	v_fma_f32 v26, -v23, v24, 1.0
	v_fmac_f32_e32 v24, v26, v24
	v_div_scale_f32 v26, vcc, 1.0, v22, 1.0
	v_mul_f32_e32 v27, v26, v24
	v_fma_f32 v32, -v23, v27, v26
	v_fmac_f32_e32 v27, v32, v24
	v_fma_f32 v23, -v23, v27, v26
	v_div_fmas_f32 v23, v23, v24, v27
	v_div_fixup_f32 v22, v23, v22, 1.0
	v_mul_f32_e32 v22, v22, v28
	v_mul_f32_e32 v20, v20, v22
	v_mul_f32_e32 v22, 0xbfb8aa3b, v29
	v_exp_f32_e32 v22, v22
	s_nop 0
	v_add_f32_e32 v22, 1.0, v22
	v_div_scale_f32 v23, s[0:1], v22, v22, 1.0
	v_rcp_f32_e32 v24, v23
	s_nop 0
	v_fma_f32 v25, -v23, v24, 1.0
	v_fmac_f32_e32 v24, v25, v24
	v_div_scale_f32 v25, vcc, 1.0, v22, 1.0
	v_mul_f32_e32 v26, v25, v24
	v_fma_f32 v27, -v23, v26, v25
	v_fmac_f32_e32 v26, v27, v24
	v_fma_f32 v23, -v23, v26, v25
	v_div_fmas_f32 v23, v23, v24, v26
	v_div_fixup_f32 v22, v23, v22, 1.0
	v_mul_f32_e32 v22, v22, v29
	v_mul_f32_e32 v21, v21, v22
	v_cvt_pk_bf16_f32 v19, v20, v21
	global_store_dwordx2 v[30:31], v[18:19], off offset:96
	v_or_b32_e32 v18, 0x80, v0
	v_mov_b32_e32 v19, v1
	v_lshl_add_u64 v[18:19], v[34:35], 0, v[18:19]
	global_load_dwordx2 v[18:19], v[18:19], off
	s_waitcnt vmcnt(0)
	v_lshlrev_b32_e32 v25, 16, v18
	v_and_b32_e32 v24, 0xffff0000, v18
	v_lshlrev_b32_e32 v23, 16, v19
	v_and_b32_e32 v22, 0xffff0000, v19
	global_load_dwordx4 v[18:21], v38, s[10:11] offset:256
	s_waitcnt vmcnt(0)
	v_mul_f32_e32 v14, v14, v18
	v_mul_f32_e32 v18, 0xbfb8aa3b, v25
	v_exp_f32_e32 v18, v18
	v_mul_f32_e32 v15, v15, v19
	v_mul_f32_e32 v16, v16, v20
	v_mul_f32_e32 v17, v17, v21
	v_add_f32_e32 v18, 1.0, v18
	v_div_scale_f32 v26, s[0:1], v18, v18, 1.0
	v_rcp_f32_e32 v27, v26
	s_nop 0
	v_fma_f32 v28, -v26, v27, 1.0
	v_fmac_f32_e32 v27, v28, v27
	v_div_scale_f32 v28, vcc, 1.0, v18, 1.0
	v_mul_f32_e32 v29, v28, v27
	v_fma_f32 v32, -v26, v29, v28
	v_fmac_f32_e32 v29, v32, v27
	v_fma_f32 v26, -v26, v29, v28
	v_div_fmas_f32 v26, v26, v27, v29
	v_div_fixup_f32 v18, v26, v18, 1.0
	v_mul_f32_e32 v18, v18, v25
	v_mul_f32_e32 v14, v14, v18
	v_mul_f32_e32 v18, 0xbfb8aa3b, v24
	v_exp_f32_e32 v18, v18
	s_nop 0
	v_add_f32_e32 v18, 1.0, v18
	v_div_scale_f32 v19, s[0:1], v18, v18, 1.0
	v_rcp_f32_e32 v25, v19
	s_nop 0
	v_fma_f32 v26, -v19, v25, 1.0
	v_fmac_f32_e32 v25, v26, v25
	v_div_scale_f32 v26, vcc, 1.0, v18, 1.0
	v_mul_f32_e32 v27, v26, v25
	v_fma_f32 v28, -v19, v27, v26
	v_fmac_f32_e32 v27, v28, v25
	v_fma_f32 v19, -v19, v27, v26
	v_div_fmas_f32 v19, v19, v25, v27
	v_div_fixup_f32 v18, v19, v18, 1.0
	v_mul_f32_e32 v18, v18, v24
	v_mul_f32_e32 v15, v15, v18
	v_mul_f32_e32 v18, 0xbfb8aa3b, v23
	v_exp_f32_e32 v18, v18
	v_cvt_pk_bf16_f32 v14, v14, v15
	s_nop 0
	v_add_f32_e32 v18, 1.0, v18
	v_div_scale_f32 v19, s[0:1], v18, v18, 1.0
	v_rcp_f32_e32 v20, v19
	s_nop 0
	v_fma_f32 v24, -v19, v20, 1.0
	v_fmac_f32_e32 v20, v24, v20
	v_div_scale_f32 v24, vcc, 1.0, v18, 1.0
	v_mul_f32_e32 v25, v24, v20
	v_fma_f32 v26, -v19, v25, v24
	v_fmac_f32_e32 v25, v26, v20
	v_fma_f32 v19, -v19, v25, v24
	v_div_fmas_f32 v19, v19, v20, v25
	v_div_fixup_f32 v18, v19, v18, 1.0
	v_mul_f32_e32 v18, v18, v23
	v_mul_f32_e32 v16, v16, v18
	v_mul_f32_e32 v18, 0xbfb8aa3b, v22
	v_exp_f32_e32 v18, v18
	s_nop 0
	v_add_f32_e32 v18, 1.0, v18
	v_div_scale_f32 v19, s[0:1], v18, v18, 1.0
	v_rcp_f32_e32 v20, v19
	s_nop 0
	v_fma_f32 v21, -v19, v20, 1.0
	v_fmac_f32_e32 v20, v21, v20
	v_div_scale_f32 v21, vcc, 1.0, v18, 1.0
	v_mul_f32_e32 v23, v21, v20
	v_fma_f32 v24, -v19, v23, v21
	v_fmac_f32_e32 v23, v24, v20
	v_fma_f32 v19, -v19, v23, v21
	v_div_fmas_f32 v19, v19, v20, v23
	v_div_fixup_f32 v18, v19, v18, 1.0
	v_mul_f32_e32 v18, v18, v22
	v_mul_f32_e32 v17, v17, v18
	v_cvt_pk_bf16_f32 v15, v16, v17
	global_store_dwordx2 v[30:31], v[14:15], off offset:128
	v_or_b32_e32 v14, 0xa0, v0
	v_mov_b32_e32 v15, v1
	v_lshl_add_u64 v[14:15], v[34:35], 0, v[14:15]
	global_load_dwordx2 v[14:15], v[14:15], off
	s_waitcnt vmcnt(0)
	v_lshlrev_b32_e32 v18, 16, v14
	v_and_b32_e32 v19, 0xffff0000, v14
	v_lshlrev_b32_e32 v20, 16, v15
	v_and_b32_e32 v21, 0xffff0000, v15
	global_load_dwordx4 v[14:17], v38, s[10:11] offset:320
	s_waitcnt vmcnt(0)
; DI unsigned pack2(float lo, float hi) { unsigned r; asm("v_cvt_pk_bf16_f32 %0, %1, %2" : "=v"(r) : "v"(lo), "v"(hi)); return r; }
; DI float lo2f(unsigned u) { return __uint_as_float(u << 16); }
; DI float hi2f(unsigned u) { return __uint_as_float(u & 0xffff0000u); }
; DI float sigmoidf_(float x) { return 1.f / (1.f + __expf(-x)); }
; DI void gla_pass3(int item, const bf16_t* __restrict__ z, const float* __restrict__ w_up, const float* __restrict__ b_alpha,
;                   const float* __restrict__ Sbuf, const float* __restrict__ gw, bf16_t* __restrict__ mix, char* smem) {
;     ...
;     for (int dt = 0; dt < 8; ++dt) {
;       const int dv = dt * 16 + 4 * g, col = h * 128 + dv;
;       const u32x2 gq = *(const u32x2*)(z + (tok0 + iq) * ABP + ZG + col);
;       const float gg[4] = {lo2f(gq[0]), hi2f(gq[0]), lo2f(gq[1]), hi2f(gq[1])};
;       const f32x4 w = *(const f32x4*)(gw + dv);
;       float y[4];
; #pragma unroll
;       for (int e = 0; e < 4; ++e) y[e] = o[0][dt][e] * r * w[e] * (gg[e] * sigmoidf_(gg[e]));
;       u32x2 ov; ov[0] = pack2(y[0], y[1]); ov[1] = pack2(y[2], y[3]);
;       *(u32x2*)(mix + (tok0 + iq) * DM + col) = ov;
;     }
	v_mul_f32_e32 v10, v10, v14
	v_mul_f32_e32 v14, 0xbfb8aa3b, v18
	v_exp_f32_e32 v14, v14
	v_mul_f32_e32 v11, v11, v15
	v_mul_f32_e32 v12, v12, v16
	v_mul_f32_e32 v13, v13, v17
	v_add_f32_e32 v14, 1.0, v14
	v_div_scale_f32 v22, s[0:1], v14, v14, 1.0
	v_rcp_f32_e32 v23, v22
	s_nop 0
	v_fma_f32 v24, -v22, v23, 1.0
	v_fmac_f32_e32 v23, v24, v23
	v_div_scale_f32 v24, vcc, 1.0, v14, 1.0
	v_mul_f32_e32 v25, v24, v23
	v_fma_f32 v26, -v22, v25, v24
	v_fmac_f32_e32 v25, v26, v23
	v_fma_f32 v22, -v22, v25, v24
	v_div_fmas_f32 v22, v22, v23, v25
	v_div_fixup_f32 v14, v22, v14, 1.0
	v_mul_f32_e32 v14, v14, v18
	v_mul_f32_e32 v10, v10, v14
	v_mul_f32_e32 v14, 0xbfb8aa3b, v19
	v_exp_f32_e32 v14, v14
	s_nop 0
	v_add_f32_e32 v14, 1.0, v14
	v_div_scale_f32 v15, s[0:1], v14, v14, 1.0
	v_rcp_f32_e32 v18, v15
	s_nop 0
	v_fma_f32 v22, -v15, v18, 1.0
	v_fmac_f32_e32 v18, v22, v18
	v_div_scale_f32 v22, vcc, 1.0, v14, 1.0
	v_mul_f32_e32 v23, v22, v18
	v_fma_f32 v24, -v15, v23, v22
	v_fmac_f32_e32 v23, v24, v18
	v_fma_f32 v15, -v15, v23, v22
	v_div_fmas_f32 v15, v15, v18, v23
	v_div_fixup_f32 v14, v15, v14, 1.0
	v_mul_f32_e32 v14, v14, v19
	v_mul_f32_e32 v11, v11, v14
	v_mul_f32_e32 v14, 0xbfb8aa3b, v20
	v_exp_f32_e32 v14, v14
	v_cvt_pk_bf16_f32 v10, v10, v11
	s_nop 0
	v_add_f32_e32 v14, 1.0, v14
	v_div_scale_f32 v15, s[0:1], v14, v14, 1.0
	v_rcp_f32_e32 v16, v15
	s_nop 0
	v_fma_f32 v18, -v15, v16, 1.0
	v_fmac_f32_e32 v16, v18, v16
	v_div_scale_f32 v18, vcc, 1.0, v14, 1.0
	v_mul_f32_e32 v19, v18, v16
	v_fma_f32 v22, -v15, v19, v18
	v_fmac_f32_e32 v19, v22, v16
	v_fma_f32 v15, -v15, v19, v18
	v_div_fmas_f32 v15, v15, v16, v19
	v_div_fixup_f32 v14, v15, v14, 1.0
	v_mul_f32_e32 v14, v14, v20
	v_mul_f32_e32 v12, v12, v14
	v_mul_f32_e32 v14, 0xbfb8aa3b, v21
	v_exp_f32_e32 v14, v14
	s_nop 0
	v_add_f32_e32 v14, 1.0, v14
	v_div_scale_f32 v15, s[0:1], v14, v14, 1.0
	v_rcp_f32_e32 v16, v15
	s_nop 0
	v_fma_f32 v17, -v15, v16, 1.0
	v_fmac_f32_e32 v16, v17, v16
	v_div_scale_f32 v17, vcc, 1.0, v14, 1.0
	v_mul_f32_e32 v18, v17, v16
	v_fma_f32 v19, -v15, v18, v17
	v_fmac_f32_e32 v18, v19, v16
	v_fma_f32 v15, -v15, v18, v17
	v_div_fmas_f32 v15, v15, v16, v18
	v_div_fixup_f32 v14, v15, v14, 1.0
	v_mul_f32_e32 v14, v14, v21
	v_mul_f32_e32 v13, v13, v14
	v_cvt_pk_bf16_f32 v11, v12, v13
	global_store_dwordx2 v[30:31], v[10:11], off offset:160
	v_or_b32_e32 v10, 0xc0, v0
	v_mov_b32_e32 v11, v1
	v_lshl_add_u64 v[10:11], v[34:35], 0, v[10:11]
	global_load_dwordx2 v[10:11], v[10:11], off
	v_or_b32_e32 v0, 0xe0, v0
	s_waitcnt vmcnt(0)
	v_lshlrev_b32_e32 v14, 16, v10
	v_and_b32_e32 v15, 0xffff0000, v10
	v_lshlrev_b32_e32 v16, 16, v11
	v_and_b32_e32 v17, 0xffff0000, v11
	global_load_dwordx4 v[10:13], v38, s[10:11] offset:384
	s_waitcnt vmcnt(0)
; DI unsigned pack2(float lo, float hi) { unsigned r; asm("v_cvt_pk_bf16_f32 %0, %1, %2" : "=v"(r) : "v"(lo), "v"(hi)); return r; }
; DI float lo2f(unsigned u) { return __uint_as_float(u << 16); }
; DI float hi2f(unsigned u) { return __uint_as_float(u & 0xffff0000u); }
; DI float sigmoidf_(float x) { return 1.f / (1.f + __expf(-x)); }
; DI void gla_pass3(int item, const bf16_t* __restrict__ z, const float* __restrict__ w_up, const float* __restrict__ b_alpha,
;                   const float* __restrict__ Sbuf, const float* __restrict__ gw, bf16_t* __restrict__ mix, char* smem) {
;     ...
;     for (int dt = 0; dt < 8; ++dt) {
;       const int dv = dt * 16 + 4 * g, col = h * 128 + dv;
;       const u32x2 gq = *(const u32x2*)(z + (tok0 + iq) * ABP + ZG + col);
;       const float gg[4] = {lo2f(gq[0]), hi2f(gq[0]), lo2f(gq[1]), hi2f(gq[1])};
;       const f32x4 w = *(const f32x4*)(gw + dv);
;       float y[4];
; #pragma unroll
;       for (int e = 0; e < 4; ++e) y[e] = o[0][dt][e] * r * w[e] * (gg[e] * sigmoidf_(gg[e]));
;       u32x2 ov; ov[0] = pack2(y[0], y[1]); ov[1] = pack2(y[2], y[3]);
;       *(u32x2*)(mix + (tok0 + iq) * DM + col) = ov;
;     }
; __global__ void __launch_bounds__(256, 2) mega(Params p) {
;     ...
;       for (int it = blockIdx.x; it < 1024; it += gridDim.x) gla_pass3(it, zb, p.in[8] + (size_t)j * 16 * 512, p.in[9] + (size_t)j * 512, Ubuf, p.in[10] + j * 128, mix, smem);
	v_mul_f32_e32 v6, v6, v10
	v_mul_f32_e32 v10, 0xbfb8aa3b, v14
	v_exp_f32_e32 v10, v10
	v_mul_f32_e32 v7, v7, v11
	v_mul_f32_e32 v8, v8, v12
	v_mul_f32_e32 v9, v9, v13
	v_add_f32_e32 v10, 1.0, v10
	v_div_scale_f32 v18, s[0:1], v10, v10, 1.0
	v_rcp_f32_e32 v19, v18
	s_nop 0
	v_fma_f32 v20, -v18, v19, 1.0
	v_fmac_f32_e32 v19, v20, v19
	v_div_scale_f32 v20, vcc, 1.0, v10, 1.0
	v_mul_f32_e32 v21, v20, v19
	v_fma_f32 v22, -v18, v21, v20
	v_fmac_f32_e32 v21, v22, v19
	v_fma_f32 v18, -v18, v21, v20
	v_div_fmas_f32 v18, v18, v19, v21
	v_div_fixup_f32 v10, v18, v10, 1.0
	v_mul_f32_e32 v10, v10, v14
	v_mul_f32_e32 v6, v6, v10
	v_mul_f32_e32 v10, 0xbfb8aa3b, v15
	v_exp_f32_e32 v10, v10
	s_nop 0
	v_add_f32_e32 v10, 1.0, v10
	v_div_scale_f32 v11, s[0:1], v10, v10, 1.0
	v_rcp_f32_e32 v14, v11
	s_nop 0
	v_fma_f32 v18, -v11, v14, 1.0
	v_fmac_f32_e32 v14, v18, v14
	v_div_scale_f32 v18, vcc, 1.0, v10, 1.0
	v_mul_f32_e32 v19, v18, v14
	v_fma_f32 v20, -v11, v19, v18
	v_fmac_f32_e32 v19, v20, v14
	v_fma_f32 v11, -v11, v19, v18
	v_div_fmas_f32 v11, v11, v14, v19
	v_div_fixup_f32 v10, v11, v10, 1.0
	v_mul_f32_e32 v10, v10, v15
	v_mul_f32_e32 v7, v7, v10
	v_mul_f32_e32 v10, 0xbfb8aa3b, v16
	v_exp_f32_e32 v10, v10
	v_cvt_pk_bf16_f32 v6, v6, v7
	s_nop 0
	v_add_f32_e32 v10, 1.0, v10
	v_div_scale_f32 v11, s[0:1], v10, v10, 1.0
	v_rcp_f32_e32 v12, v11
	s_nop 0
	v_fma_f32 v14, -v11, v12, 1.0
	v_fmac_f32_e32 v12, v14, v12
	v_div_scale_f32 v14, vcc, 1.0, v10, 1.0
	v_mul_f32_e32 v15, v14, v12
	v_fma_f32 v18, -v11, v15, v14
	v_fmac_f32_e32 v15, v18, v12
	v_fma_f32 v11, -v11, v15, v14
	v_div_fmas_f32 v11, v11, v12, v15
	v_div_fixup_f32 v10, v11, v10, 1.0
	v_mul_f32_e32 v10, v10, v16
	v_mul_f32_e32 v8, v8, v10
	v_mul_f32_e32 v10, 0xbfb8aa3b, v17
	v_exp_f32_e32 v10, v10
	s_nop 0
	v_add_f32_e32 v10, 1.0, v10
	v_div_scale_f32 v11, s[0:1], v10, v10, 1.0
	v_rcp_f32_e32 v12, v11
	s_nop 0
	v_fma_f32 v13, -v11, v12, 1.0
	v_fmac_f32_e32 v12, v13, v12
	v_div_scale_f32 v13, vcc, 1.0, v10, 1.0
	v_mul_f32_e32 v14, v13, v12
	v_fma_f32 v15, -v11, v14, v13
	v_fmac_f32_e32 v14, v15, v12
	v_fma_f32 v11, -v11, v14, v13
	v_div_fmas_f32 v11, v11, v12, v14
	v_div_fixup_f32 v10, v11, v10, 1.0
	v_mul_f32_e32 v10, v10, v17
	v_mul_f32_e32 v9, v9, v10
	v_cvt_pk_bf16_f32 v7, v8, v9
	global_store_dwordx2 v[30:31], v[6:7], off offset:192
	v_lshl_add_u64 v[6:7], v[34:35], 0, v[0:1]
	global_load_dwordx2 v[6:7], v[6:7], off
	s_waitcnt vmcnt(0)
	v_lshlrev_b32_e32 v12, 16, v6
	v_and_b32_e32 v11, 0xffff0000, v6
	v_lshlrev_b32_e32 v10, 16, v7
	v_and_b32_e32 v0, 0xffff0000, v7
	global_load_dwordx4 v[6:9], v38, s[10:11] offset:448
	s_waitcnt vmcnt(0)
	v_mul_f32_e32 v2, v2, v6
	v_mul_f32_e32 v6, 0xbfb8aa3b, v12
	v_exp_f32_e32 v6, v6
	v_mul_f32_e32 v3, v3, v7
	v_mul_f32_e32 v4, v4, v8
	v_mul_f32_e32 v5, v5, v9
	v_add_f32_e32 v6, 1.0, v6
	v_div_scale_f32 v13, s[0:1], v6, v6, 1.0
	v_rcp_f32_e32 v14, v13
	s_nop 0
	v_fma_f32 v15, -v13, v14, 1.0
	v_fmac_f32_e32 v14, v15, v14
	v_div_scale_f32 v15, vcc, 1.0, v6, 1.0
	v_mul_f32_e32 v16, v15, v14
	v_fma_f32 v17, -v13, v16, v15
	v_fmac_f32_e32 v16, v17, v14
	v_fma_f32 v13, -v13, v16, v15
	v_div_fmas_f32 v13, v13, v14, v16
	v_div_fixup_f32 v6, v13, v6, 1.0
	v_mul_f32_e32 v6, v6, v12
	v_mul_f32_e32 v2, v2, v6
	v_mul_f32_e32 v6, 0xbfb8aa3b, v11
	v_exp_f32_e32 v6, v6
	s_nop 0
	v_add_f32_e32 v6, 1.0, v6
	v_div_scale_f32 v7, s[0:1], v6, v6, 1.0
	v_rcp_f32_e32 v12, v7
	s_nop 0
	v_fma_f32 v13, -v7, v12, 1.0
	v_fmac_f32_e32 v12, v13, v12
	v_div_scale_f32 v13, vcc, 1.0, v6, 1.0
	v_mul_f32_e32 v14, v13, v12
	v_fma_f32 v15, -v7, v14, v13
	v_fmac_f32_e32 v14, v15, v12
	v_fma_f32 v7, -v7, v14, v13
	v_div_fmas_f32 v7, v7, v12, v14
	v_div_fixup_f32 v6, v7, v6, 1.0
	v_mul_f32_e32 v6, v6, v11
	v_mul_f32_e32 v3, v3, v6
	v_mul_f32_e32 v6, 0xbfb8aa3b, v10
	v_exp_f32_e32 v6, v6
	v_cvt_pk_bf16_f32 v2, v2, v3
	s_nop 0
	v_add_f32_e32 v6, 1.0, v6
	v_div_scale_f32 v7, s[0:1], v6, v6, 1.0
	v_rcp_f32_e32 v8, v7
	s_nop 0
	v_fma_f32 v11, -v7, v8, 1.0
	v_fmac_f32_e32 v8, v11, v8
	v_div_scale_f32 v11, vcc, 1.0, v6, 1.0
	v_mul_f32_e32 v12, v11, v8
	v_fma_f32 v13, -v7, v12, v11
	v_fmac_f32_e32 v12, v13, v8
	v_fma_f32 v7, -v7, v12, v11
	v_div_fmas_f32 v7, v7, v8, v12
	v_div_fixup_f32 v6, v7, v6, 1.0
	v_mul_f32_e32 v6, v6, v10
	v_mul_f32_e32 v4, v4, v6
	v_mul_f32_e32 v6, 0xbfb8aa3b, v0
	v_exp_f32_e32 v6, v6
	s_nop 0
	v_add_f32_e32 v6, 1.0, v6
	v_div_scale_f32 v7, s[0:1], v6, v6, 1.0
	v_rcp_f32_e32 v8, v7
	v_readlane_b32 s0, v253, 52
	s_add_i32 s12, s12, s100
	s_cmp_ge_i32 s12, s101
	v_fma_f32 v9, -v7, v8, 1.0
	v_fmac_f32_e32 v8, v9, v8
	v_div_scale_f32 v9, vcc, 1.0, v6, 1.0
	v_mul_f32_e32 v10, v9, v8
	v_fma_f32 v11, -v7, v10, v9
	v_fmac_f32_e32 v10, v11, v8
	v_fma_f32 v7, -v7, v10, v9
	v_div_fmas_f32 v7, v7, v8, v10
	v_div_fixup_f32 v6, v7, v6, 1.0
	v_mul_f32_e32 v0, v6, v0
	v_mul_f32_e32 v0, v5, v0
	v_cvt_pk_bf16_f32 v3, v4, v0
	global_store_dwordx2 v[30:31], v[2:3], off offset:224
	v_readlane_b32 s1, v253, 53
	s_cbranch_scc1 .LBB0_960
